# v037
# baseline (speedup 1.0000x reference)
.LBB0_298:
	s_or_b64 exec, exec, s[8:9]
	v_mov_b32_e32 v0, s51
	s_waitcnt lgkmcnt(0)
	s_barrier
	ds_read_b32 v0, v0
	s_waitcnt lgkmcnt(0)
	v_cmp_gt_i32_e32 vcc, 0, v0
	v_readfirstlane_b32 s2, v0
	s_cbranch_vccnz .LBB0_340
	s_mul_hi_u32 s3, s2, 0xaaaaaaab
	s_lshr_b32 s3, s3, 8
	s_mul_i32 s5, s3, 0x180
	s_sub_i32 s5, s2, s5
	s_lshr_b32 s7, s5, 2
	s_and_b32 s7, s7, 0x78
	s_sub_i32 s8, s7, s3
	s_and_b32 s2, s5, 32
	s_add_i32 s8, s8, 7
	s_add_i32 s7, s7, s3
	s_cmp_eq_u32 s2, 0
	s_cselect_b32 s3, s7, s8
	s_mul_hi_i32 s7, s3, 0x2aaaaaab
	s_lshr_b32 s8, s7, 31
	s_mul_hi_i32 s21, s3, 0xd5555555
	s_add_i32 s7, s7, s8
	s_lshr_b32 s2, s21, 31
	s_mul_i32 s7, s7, 6
	s_add_i32 s21, s21, s2
	s_sub_i32 s3, s3, s7
	s_add_i32 s2, s21, 15
	s_and_b32 s5, s5, 31
	s_lshl_b32 s7, s3, 5
	s_cmp_lt_i32 s3, 4
	s_cselect_b32 s7, s7, 0
	s_lshl_b32 s8, s2, 4
	s_add_i32 s8, s8, 0
	s_add_i32 s8, s8, 0x20000
	v_mov_b32_e32 v0, s8
	s_max_i32 s3, s3, 3
	s_waitcnt vmcnt(0)
	ds_read_b96 v[2:4], v0
	s_or_b32 s22, s5, s7
	s_add_i32 s18, s3, -3
	s_cmp_eq_u32 s18, 1
	s_movk_i32 s3, 0x5000
	v_readfirstlane_b32 s9, v195
	s_cselect_b32 s25, 0x4000, s3
	s_bfe_u32 s5, s9, 0x20006
	s_lshl_b32 s10, s22, 7
	s_lshl_b32 s11, s5, 5
	s_lshr_b32 s3, s9, 6
	s_lshr_b32 s7, s9, 8
	s_or_b32 s23, s11, s10
	s_mul_i32 s12, s2, 0x600000
	s_waitcnt lgkmcnt(0)
	v_readfirstlane_b32 s8, v2
	s_mul_hi_i32 s11, s2, 0x600000
	s_add_u32 s16, s63, s12
	s_addc_u32 s17, s4, s11
	s_sub_i32 s11, s10, s8
	s_or_b32 s24, s10, 0x7f
	s_ashr_i32 s11, s11, 6
	s_add_i32 s8, s8, s24
	s_lshl_b32 s80, s7, 7
	s_add_i32 s33, s21, 16
	s_max_i32 s11, s11, 0
	s_ashr_i32 s12, s8, 6
	s_cmpk_lt_u32 s9, 0x100
	s_cselect_b64 s[8:9], -1, 0
	s_and_b64 s[14:15], s[8:9], exec
	v_readfirstlane_b32 s13, v3
	v_readfirstlane_b32 s19, v4
	s_cselect_b32 s14, 16, 32
	v_mov_b32_e32 v0, v195
	v_mov_b32_e32 v181, v194
	s_cselect_b32 s13, s13, s19
	s_add_i32 s15, s14, s2
	s_lshl_b32 s19, s5, 11
	s_cmp_eq_u32 s18, 0
	v_and_b32_e32 v0, 31, v181
	s_cselect_b32 s14, 0, s25
	v_or_b32_e32 v10, s23, v0
	v_add_u32_e32 v164, s14, v10
	v_ashrrev_i32_e32 v165, 31, v164
	v_ashrrev_i32_e32 v186, 5, v181
	v_lshlrev_b64 v[2:3], 8, v[164:165]
	v_lshl_add_u64 v[2:3], s[16:17], 0, v[2:3]
	v_lshlrev_b32_e32 v166, 3, v186
	v_lshl_add_u64 v[2:3], v[2:3], 0, s[80:81]
	v_ashrrev_i32_e32 v167, 31, v166
	v_lshl_add_u64 v[2:3], v[166:167], 1, v[2:3]
	global_load_dwordx4 v[144:147], v[2:3], off
	global_load_dwordx4 v[148:151], v[2:3], off offset:32
	global_load_dwordx4 v[152:155], v[2:3], off offset:64
	global_load_dwordx4 v[156:159], v[2:3], off offset:96
	v_lshlrev_b32_e32 v3, 2, v181
	v_lshl_add_u32 v2, s7, 3, v186
	v_and_b32_e32 v3, 12, v3
	v_bfe_u32 v4, v181, 2, 2
	v_lshlrev_b32_e32 v0, 8, v0
	v_bitop3_b32 v5, v3, v2, v4 bitop3:0x36
	v_lshl_add_u32 v182, v5, 4, v0
	v_add_u32_e32 v5, 2, v2
	v_bitop3_b32 v5, v3, v5, v4 bitop3:0x36
	v_lshl_add_u32 v183, v5, 4, v0
	v_add_u32_e32 v5, 4, v2
	v_add_u32_e32 v2, 6, v2
	v_bitop3_b32 v5, v3, v5, v4 bitop3:0x36
	v_bitop3_b32 v2, v3, v2, v4 bitop3:0x36
	v_lshl_add_u32 v184, v5, 4, v0
	v_lshl_add_u32 v185, v2, 4, v0
	v_ashrrev_i32_e32 v0, 4, v181
	v_lshlrev_b32_e32 v3, 1, v0
	v_and_b32_e32 v7, 12, v181
	v_lshlrev_b32_e32 v11, 2, v186
	v_and_b32_e32 v3, 2, v3
	v_bfe_u32 v5, v181, 1, 1
	v_lshlrev_b32_e32 v8, 3, v181
	v_and_or_b32 v9, v186, 3, v7
	v_or_b32_e32 v6, v3, v5
	v_and_b32_e32 v12, 8, v8
	v_or_b32_e32 v8, v11, v4
	v_bitop3_b32 v3, v3, v9, v5 bitop3:0x36
	v_lshlrev_b32_e32 v8, 8, v8
	v_lshlrev_b32_e32 v3, 4, v3
	v_or3_b32 v187, v3, v8, v12
	v_add_u32_e32 v3, 8, v11
	v_or_b32_e32 v4, v3, v4
	v_bfe_u32 v3, v3, 2, 2
	v_lshlrev_b32_e32 v13, 8, v4
	v_bitop3_b32 v4, v3, v6, v7 bitop3:0x36
	v_lshlrev_b32_e32 v4, 4, v4
	v_or3_b32 v188, v4, v13, v12
	v_or_b32_e32 v4, 4, v6
	v_bitop3_b32 v4, v3, v4, v7 bitop3:0x36
	v_bitop3_b32 v5, v6, v9, 4 bitop3:0x36
	v_lshlrev_b32_e32 v4, 4, v4
	v_lshlrev_b32_e32 v5, 4, v5
	v_or3_b32 v190, v4, v13, v12
	v_or_b32_e32 v4, 8, v6
	v_or3_b32 v189, v5, v8, v12
	v_bitop3_b32 v5, v6, v9, 8 bitop3:0x36
	v_bitop3_b32 v4, v3, v4, v7 bitop3:0x36
	v_lshlrev_b32_e32 v5, 4, v5
	v_lshlrev_b32_e32 v4, 4, v4
	v_or3_b32 v191, v5, v8, v12
	v_or3_b32 v192, v4, v13, v12
	v_or_b32_e32 v4, 12, v6
	v_bitop3_b32 v5, v6, v9, 12 bitop3:0x36
	v_cvt_f32_i32_e32 v6, s33
	v_and_b32_e32 v2, 15, v181
	v_bitop3_b32 v14, v3, v4, v7 bitop3:0x36
	v_lshlrev_b32_e32 v5, 4, v5
	v_mul_f32_e32 v3, -0.5, v6
	v_exp_f32_e32 v15, v3
	v_lshl_add_u32 v3, v0, 7, s19
	v_lshlrev_b32_e32 v0, 5, v0
	v_lshlrev_b32_e32 v2, 3, v2
	v_or3_b32 v193, v5, v8, v12
	v_xor_b32_e32 v5, v0, v2
	v_xor_b32_e32 v2, 8, v5
	s_movk_i32 s17, 0x200
	v_add3_u32 v2, v3, v2, s17
	v_xor_b32_e32 v4, 16, v5
	s_movk_i32 s17, 0x400
	v_add_u32_e32 v0, v3, v5
	v_add3_u32 v4, v3, v4, s17
	v_xor_b32_e32 v5, 24, v5
	s_movk_i32 s17, 0x600
	v_add3_u32 v6, v3, v5, s17
	s_mul_hi_i32 s16, s15, 0x600000
	s_mul_i32 s15, s15, 0x600000
	s_cselect_b32 s17, 0xff, 63
	s_add_u32 s15, s63, s15
	s_addc_u32 s16, s4, s16
	s_lshl_b32 s14, s14, 8
	s_add_u32 s33, s15, s14
	s_addc_u32 s37, s16, 0
	s_lshr_b32 s44, s11, 1
	s_ashr_i32 s11, s10, 31
	s_lshl_b64 s[14:15], s[10:11], 8
	s_add_u32 s14, s33, s14
	s_addc_u32 s15, s37, s15
	s_lshl_b32 s11, s7, 14
	s_add_i32 s45, s11, 0
	s_lshl_b32 s11, s5, 12
	s_add_i32 s45, s45, s11
	v_lshlrev_b32_e32 v168, 1, v0
	v_lshlrev_b32_e32 v170, 1, v2
	v_lshlrev_b32_e32 v172, 1, v4
	v_lshlrev_b32_e32 v174, 1, v6
	v_mov_b32_e32 v169, v1
	v_mov_b32_e32 v171, v1
	v_mov_b32_e32 v173, v1
	v_mov_b32_e32 v175, v1
	s_mov_b32 m0, s45
	s_nop 0
	global_load_lds_dwordx4 v168, s[14:15]
	s_add_i32 m0, s45, 0x400
	s_nop 0
	global_load_lds_dwordx4 v170, s[14:15]
	s_add_i32 m0, s45, 0x800
	s_nop 0
	global_load_lds_dwordx4 v172, s[14:15]
	s_add_i32 m0, s45, 0xc00
	s_nop 0
	global_load_lds_dwordx4 v174, s[14:15]
	s_add_u32 s14, s14, 0x4000
	s_addc_u32 s15, s15, 0
	s_add_i32 m0, s45, 0x8000
	s_nop 0
	global_load_lds_dwordx4 v168, s[14:15]
	s_add_i32 m0, s45, 0x8400
	s_nop 0
	global_load_lds_dwordx4 v170, s[14:15]
	s_add_i32 m0, s45, 0x8800
	s_nop 0
	global_load_lds_dwordx4 v172, s[14:15]
	s_add_i32 m0, s45, 0x8c00
	s_nop 0
	global_load_lds_dwordx4 v174, s[14:15]
	s_waitcnt vmcnt(10)
	v_and_b32_e32 v7, 0xffff0000, v148
	v_and_b32_e32 v5, 0xffff0000, v144
	v_lshlrev_b32_e32 v3, 16, v144
	v_mul_f32_e32 v5, v5, v5
	v_fmac_f32_e32 v5, v3, v3
	v_lshlrev_b32_e32 v3, 16, v145
	v_fmac_f32_e32 v5, v3, v3
	v_and_b32_e32 v3, 0xffff0000, v145
	v_fmac_f32_e32 v5, v3, v3
	v_lshlrev_b32_e32 v3, 16, v146
	v_fmac_f32_e32 v5, v3, v3
	v_and_b32_e32 v3, 0xffff0000, v146
	v_fmac_f32_e32 v5, v3, v3
	v_lshlrev_b32_e32 v3, 16, v147
	v_fmac_f32_e32 v5, v3, v3
	v_and_b32_e32 v3, 0xffff0000, v147
	v_fmac_f32_e32 v5, v3, v3
	v_lshlrev_b32_e32 v3, 16, v148
	v_mul_f32_e32 v7, v7, v7
	v_fmac_f32_e32 v7, v3, v3
	v_lshlrev_b32_e32 v3, 16, v149
	v_fmac_f32_e32 v7, v3, v3
	v_and_b32_e32 v3, 0xffff0000, v149
	v_fmac_f32_e32 v7, v3, v3
	v_lshlrev_b32_e32 v3, 16, v150
	v_fmac_f32_e32 v7, v3, v3
	v_and_b32_e32 v3, 0xffff0000, v150
	v_fmac_f32_e32 v7, v3, v3
	v_lshlrev_b32_e32 v3, 16, v151
	v_fmac_f32_e32 v7, v3, v3
	v_and_b32_e32 v3, 0xffff0000, v151
	v_fmac_f32_e32 v7, v3, v3
	v_add_f32_e32 v3, v5, v7
	s_waitcnt vmcnt(9)
	v_and_b32_e32 v7, 0xffff0000, v152
	v_lshlrev_b32_e32 v5, 16, v152
	v_mul_f32_e32 v7, v7, v7
	v_fmac_f32_e32 v7, v5, v5
	v_lshlrev_b32_e32 v5, 16, v153
	v_fmac_f32_e32 v7, v5, v5
	v_and_b32_e32 v5, 0xffff0000, v153
	v_fmac_f32_e32 v7, v5, v5
	v_lshlrev_b32_e32 v5, 16, v154
	v_fmac_f32_e32 v7, v5, v5
	v_and_b32_e32 v5, 0xffff0000, v154
	v_fmac_f32_e32 v7, v5, v5
	v_lshlrev_b32_e32 v5, 16, v155
	v_fmac_f32_e32 v7, v5, v5
	v_and_b32_e32 v5, 0xffff0000, v155
	v_fmac_f32_e32 v7, v5, v5
	s_waitcnt vmcnt(8)
	v_and_b32_e32 v5, 0xffff0000, v156
	v_add_f32_e32 v16, v3, v7
	v_lshlrev_b32_e32 v3, 16, v156
	v_mul_f32_e32 v17, v5, v5
	v_fmac_f32_e32 v17, v3, v3
	v_lshlrev_b32_e32 v3, 16, v157
	v_fmac_f32_e32 v17, v3, v3
	v_and_b32_e32 v3, 0xffff0000, v157
	v_fmac_f32_e32 v17, v3, v3
	v_lshlrev_b32_e32 v3, 16, v158
	v_fmac_f32_e32 v17, v3, v3
	v_mov_b32_e32 v3, v1
	v_mov_b32_e32 v5, v1
	v_mov_b32_e32 v7, v1
	v_and_b32_e32 v0, 0xffff0000, v158
	v_fmac_f32_e32 v17, v0, v0
	v_lshlrev_b32_e32 v0, 16, v159
	v_fmac_f32_e32 v17, v0, v0
	v_and_b32_e32 v0, 0xffff0000, v159
	v_fmac_f32_e32 v17, v0, v0
	v_add_f32_e32 v0, v16, v17
	v_mov_b32_e32 v2, v0
	s_nop 1
	v_permlane32_swap_b32_e32 v0, v2
	v_add_f32_e32 v0, v0, v2
	v_mul_f32_e32 v2, 0x4f800000, v0
	v_cmp_gt_f32_e32 vcc, s65, v0
	v_lshlrev_b32_e32 v3, 4, v14
	v_or3_b32 v196, v3, v13, v12
	v_cndmask_b32_e32 v0, v0, v2, vcc
	v_sqrt_f32_e32 v2, v0
	s_min_i32 s11, s17, s12
	s_ashr_i32 s46, s11, 1
	s_lshl_b32 s11, s3, 2
	v_add_u32_e32 v3, -1, v2
	v_fma_f32 v4, -v3, v2, v0
	v_cmp_ge_f32_e64 s[38:39], 0, v4
	v_add_u32_e32 v4, 1, v2
	s_add_i32 s48, s11, 0
	v_cndmask_b32_e64 v3, v2, v3, s[38:39]
	v_fma_f32 v2, -v4, v2, v0
	v_cmp_lt_f32_e64 s[38:39], 0, v2
	s_or_b32 s47, s23, 31
	s_add_i32 s48, s48, 0x20440
	v_cndmask_b32_e64 v2, v3, v4, s[38:39]
	v_mul_f32_e32 v3, 0x37800000, v2
	v_cndmask_b32_e32 v2, v2, v3, vcc
	v_cmp_class_f32_e32 vcc, v0, v227
	s_add_i32 s49, s22, 1
	s_cmp_lt_i32 s22, s46
	v_cndmask_b32_e32 v0, v2, v0, vcc
	v_mul_f32_e32 v176, 0x3fb8aa3b, v15
	v_mul_f32_e32 v0, 0x3e3a82f9, v0
	s_cselect_b32 s11, s49, -1
	s_add_i32 s12, s22, -1
	s_or_b32 s50, s10, 1
	v_mov_b32_e32 v14, v1
	v_mov_b32_e32 v15, v1
	v_mul_f32_e32 v197, s13, v0
	v_sub_u32_e32 v198, v11, v10
	v_xor_b32_e32 v178, 0x80000000, v176
	s_cmp_gt_i32 s22, s44
	v_mov_b32_e32 v0, v1
	v_mov_b32_e32 v2, v1
	v_mov_b32_e32 v3, v1
	v_mov_b32_e32 v4, v1
	v_mov_b32_e32 v6, v1
	v_mov_b32_e32 v8, v1
	v_mov_b32_e32 v9, v1
	v_mov_b32_e32 v10, v1
	v_mov_b32_e32 v11, v1
	v_mov_b32_e32 v12, v1
	v_mov_b32_e32 v13, v1
	v_mov_b64_e32 v[30:31], v[14:15]
	v_mov_b64_e32 v[46:47], v[14:15]
	v_mov_b64_e32 v[62:63], v[14:15]
	v_mov_b64_e32 v[78:79], v[14:15]
	s_mov_b32 s25, 0
	v_cmp_eq_u32_e64 s[38:39], 0, v181
	s_cselect_b32 s79, s12, s11
	s_cselect_b32 s78, 1, 2
	v_mov_b32_e32 v177, v176
	v_mov_b32_e32 v179, v178
	v_mul_f32_e32 v201, 0xc27c0000, v176
	v_add_f32_e32 v201, 0x41000000, v201
	s_nop 0
	v_readfirstlane_b32 s100, v201
	v_mov_b32_e32 v201, 0
	v_mov_b32_e32 v199, 0
	s_mov_b32 s83, 0
	v_mov_b32_e32 v180, 0
	v_mov_b64_e32 v[28:29], v[12:13]
	v_mov_b64_e32 v[26:27], v[10:11]
	v_mov_b64_e32 v[24:25], v[8:9]
	v_mov_b64_e32 v[22:23], v[6:7]
	v_mov_b64_e32 v[20:21], v[4:5]
	v_mov_b64_e32 v[18:19], v[2:3]
	v_mov_b64_e32 v[16:17], v[0:1]
	v_mov_b64_e32 v[44:45], v[12:13]
	v_mov_b64_e32 v[42:43], v[10:11]
	v_mov_b64_e32 v[40:41], v[8:9]
	v_mov_b64_e32 v[38:39], v[6:7]
	v_mov_b64_e32 v[36:37], v[4:5]
	v_mov_b64_e32 v[34:35], v[2:3]
	v_mov_b64_e32 v[32:33], v[0:1]
	v_mov_b64_e32 v[60:61], v[12:13]
	v_mov_b64_e32 v[58:59], v[10:11]
	v_mov_b64_e32 v[56:57], v[8:9]
	v_mov_b64_e32 v[54:55], v[6:7]
	v_mov_b64_e32 v[52:53], v[4:5]
	v_mov_b64_e32 v[50:51], v[2:3]
	v_mov_b64_e32 v[48:49], v[0:1]
	v_mov_b64_e32 v[76:77], v[12:13]
	v_mov_b64_e32 v[74:75], v[10:11]
	v_mov_b64_e32 v[72:73], v[8:9]
	v_mov_b64_e32 v[70:71], v[6:7]
	v_mov_b64_e32 v[68:69], v[4:5]
	v_mov_b64_e32 v[66:67], v[2:3]
	v_mov_b64_e32 v[64:65], v[0:1]
	s_mov_b32 s18, s22
	s_mov_b32 s10, 0
	v_readfirstlane_b32 s101, v195
	s_cmpk_lt_u32 s101, 0x100
	s_cbranch_scc1 .Lmy_prio_lo
	s_setprio 1

.LBB0_300:
	v_subrev_co_u32_e64 v199, s[40:41], 1, v199
	s_and_b64 vcc, exec, s[40:41]
	s_mov_b32 s82, s78
	s_mov_b32 s51, s79
	s_cbranch_vccnz .LBB0_306
	s_andn2_b32 s11, 8, s83
	s_lshl_b32 s11, s11, 2
	s_add_i32 s11, s11, 0
	s_add_i32 s11, s11, 0x20440
	v_mov_b32_e32 v0, s11
	ds_read_b128 v[2:5], v0
	ds_read_b128 v[6:9], v0 offset:16
	s_cmp_eq_u32 s10, 1
	s_cselect_b32 s11, -1, 1
	s_add_i32 s11, s11, s18
	s_waitcnt lgkmcnt(0)
	v_or3_b32 v0, v2, v3, v4
	v_or3_b32 v0, v0, v5, v6
	v_or3_b32 v0, v0, v7, v8
	v_or_b32_e32 v0, v0, v9
	s_cmp_lg_u32 s10, 1
	v_readfirstlane_b32 s12, v0
	s_mov_b32 s13, -1
	s_cbranch_scc1 .LBB0_305
	s_cmp_lt_i32 s11, s44
	s_cselect_b64 s[14:15], -1, 0
	s_bitcmp0_b32 s12, 0
	s_cselect_b64 s[16:17], -1, 0
	s_or_b64 s[14:15], s[14:15], s[16:17]
	s_mov_b32 s10, 1
	s_andn2_b64 vcc, exec, s[14:15]
	s_mov_b32 s14, s11
	s_cbranch_vccnz .LBB0_304
	s_mov_b32 s11, -1
	s_mov_b32 s10, 2
	s_mov_b32 s14, s49
